# P3 second-half blocks: leftover s_nop padding deleted, gelu constant kept in a loop-invariant VGPR pair, dead high-half movs dropped
# speedup vs baseline: 1.0011x; 1.0011x over previous
; __device__ __forceinline__ unsigned cvt_pk_bf16(float lo, float hi) { unsigned r; asm volatile("v_cvt_pk_bf16_f32 %0, %1, %2" : "=v"(r) : "v"(lo), "v"(hi)); return r; }
; __device__ __forceinline__ void s5_phase(const Args& a, const Ctx& F) {
;     ...
;     for (int tile = 0; tile < 4; ++tile) {
;         bf16x8 A01[2];
; #pragma unroll
;         for (int sx = 0; sx < 2; ++sx) {
;             const int q = tile * 64 + 2 * nl + hl, t = d ? (CTXL - 1 - q) : q;
;             const float* p0 = UCP + (size_t)(b * CTXL + t) * EI + chan0 + 8 * sx;
;             f32x4 lo = *(const f32x4*)p0, hi = *(const f32x4*)(p0 + 4);
; #pragma unroll
;             for (int k = 1; k < 4; ++k) { lo += *(const f32x4*)(p0 + (size_t)k * MC * EI); hi += *(const f32x4*)(p0 + (size_t)k * MC * EI + 4); }
;             u32x4 w; w.x = cvt_pk_bf16(lo[0], lo[1]); w.y = cvt_pk_bf16(lo[2], lo[3]); w.z = cvt_pk_bf16(hi[0], hi[1]); w.w = cvt_pk_bf16(hi[2], hi[3]);
;             A01[sx] = __builtin_bit_cast(bf16x8, w);
;         }
;         S5_STATE_IN(A01[0], A01[1])
; #pragma unroll
;         for (int i = 0; i < 32; ++i) {
;             const int r = (i & 3) + 4 * (i >> 3); const bool up = (i >> 2) & 1;
;             const float sr = up ? sre1[r] : sre0[r], si = up ? sim1[r] : sim0[r];
;             const float nre = __builtin_fmaf(lr, hre, __builtin_fmaf(nli, him, sr)), nim = __builtin_fmaf(lr, him, __builtin_fmaf(li, hre, si)); hre = nre; him = nim;
;         }
.LBB0_377:
	v_add_u32_e32 v0, s6, v144
	v_cndmask_b32_e64 v0, v0, v145, s[0:1]
	v_add_u32_e32 v0, s7, v0
	v_ashrrev_i32_e32 v1, 31, v0
	v_lshlrev_b64 v[0:1], 15, v[0:1]
	v_lshl_add_u64 v[36:37], s[8:9], 0, v[0:1]
	v_add_co_u32_e32 v38, vcc, 0x1000000, v36
	v_lshl_add_u64 v[12:13], v[36:37], 0, s[10:11]
	s_nop 0
	v_addc_co_u32_e32 v39, vcc, 0, v37, vcc
	v_add_co_u32_e32 v40, vcc, s43, v36
	global_load_dwordx4 v[0:3], v[36:37], off offset:16
	global_load_dwordx4 v[4:7], v[36:37], off
	v_addc_co_u32_e32 v41, vcc, 0, v37, vcc
	v_lshl_add_u64 v[20:21], v[36:37], 0, s[16:17]
	global_load_dwordx4 v[8:11], v[38:39], off
	s_nop 0
	global_load_dwordx4 v[12:15], v[12:13], off offset:16
	v_add_co_u32_e32 v42, vcc, s46, v36
	v_lshl_add_u64 v[28:29], v[36:37], 0, s[18:19]
	global_load_dwordx4 v[16:19], v[40:41], off
	s_nop 0
	global_load_dwordx4 v[20:23], v[20:21], off offset:16
	v_addc_co_u32_e32 v43, vcc, 0, v37, vcc
	global_load_dwordx4 v[24:27], v[42:43], off
	s_nop 0
	global_load_dwordx4 v[28:31], v[28:29], off offset:16
	v_lshl_add_u64 v[44:45], v[36:37], 0, s[40:41]
	s_sub_i32 s6, s6, 64
	v_add_u32_e32 v145, 64, v145
	s_cmp_eq_u32 s6, -1
	s_waitcnt vmcnt(5)
	v_pk_add_f32 v[6:7], v[6:7], v[10:11]
	v_pk_add_f32 v[4:5], v[4:5], v[8:9]
	s_waitcnt vmcnt(4)
	v_pk_add_f32 v[2:3], v[2:3], v[14:15]
	v_pk_add_f32 v[0:1], v[0:1], v[12:13]
	s_waitcnt vmcnt(3)
	v_pk_add_f32 v[6:7], v[6:7], v[18:19]
	v_pk_add_f32 v[4:5], v[4:5], v[16:17]
	s_waitcnt vmcnt(2)
	v_pk_add_f32 v[2:3], v[2:3], v[22:23]
	v_pk_add_f32 v[0:1], v[0:1], v[20:21]
	s_waitcnt vmcnt(1)
	v_pk_add_f32 v[6:7], v[6:7], v[26:27]
	v_pk_add_f32 v[4:5], v[4:5], v[24:25]
	s_waitcnt vmcnt(0)
	v_pk_add_f32 v[2:3], v[2:3], v[30:31]
	v_pk_add_f32 v[0:1], v[0:1], v[28:29]
	v_cvt_pk_bf16_f32 v32, v4, v5
	v_cvt_pk_bf16_f32 v33, v6, v7
	v_lshl_add_u64 v[16:17], v[36:37], 0, s[22:23]
	v_cvt_pk_bf16_f32 v34, v0, v1
	v_cvt_pk_bf16_f32 v35, v2, v3
	global_load_dwordx4 v[146:149], v[36:37], off offset:48
	global_load_dwordx4 v[150:153], v[36:37], off offset:32
	global_load_dwordx4 v[166:169], v[38:39], off offset:32
	v_lshl_add_u64 v[18:19], v[36:37], 0, s[38:39]
	global_load_dwordx4 v[176:179], v[16:17], off offset:16
	global_load_dwordx4 v[180:183], v[40:41], off offset:32
	global_load_dwordx4 v[184:187], v[18:19], off offset:16
	global_load_dwordx4 v[188:191], v[42:43], off offset:32
	global_load_dwordx4 v[192:195], v[44:45], off offset:16
	v_mfma_f32_32x32x16_bf16 v[0:15], v[32:35], v[108:111], 0
	s_waitcnt vmcnt(4)
	v_add_f32_e64 v148, v148, v178
	v_add_f32_e64 v149, v149, v179
	v_mfma_f32_32x32x16_bf16 v[48:63], v[32:35], v[112:115], 0
	v_add_f32_e64 v146, v146, v176
	v_add_f32_e64 v147, v147, v177
	v_add_f32_e64 v152, v152, v168
	v_add_f32_e64 v153, v153, v169
	v_add_f32_e64 v150, v150, v166
	v_add_f32_e64 v151, v151, v167
	s_waitcnt vmcnt(2)
	v_pk_add_f32 v[148:149], v[148:149], v[186:187]
	v_pk_add_f32 v[146:147], v[146:147], v[184:185]
	v_pk_add_f32 v[152:153], v[152:153], v[182:183]
	v_pk_add_f32 v[150:151], v[150:151], v[180:181]
	v_mfma_f32_32x32x16_bf16 v[16:31], v[32:35], v[116:119], 0
	s_waitcnt vmcnt(0)
	v_add_f32_e64 v154, v148, v194
	v_add_f32_e64 v155, v149, v195
	v_add_f32_e64 v148, v146, v192
	v_add_f32_e64 v149, v147, v193
	v_pk_add_f32 v[152:153], v[152:153], v[190:191]
	v_pk_add_f32 v[150:151], v[150:151], v[188:189]
	s_nop 0
	v_cvt_pk_bf16_f32 v146, v150, v151
	v_cvt_pk_bf16_f32 v147, v152, v153
	v_mfma_f32_32x32x16_bf16 v[32:47], v[32:35], v[120:123], 0
	v_cvt_pk_bf16_f32 v148, v148, v149
	v_cvt_pk_bf16_f32 v149, v154, v155
	s_nop 0
	v_mfma_f32_32x32x16_bf16 v[0:15], v[146:149], v[124:127], v[0:15]
	v_mfma_f32_32x32x16_bf16 v[48:63], v[146:149], v[128:131], v[48:63]
	v_mfma_f32_32x32x16_bf16 v[16:31], v[146:149], v[132:135], v[16:31]
	v_mfma_f32_32x32x16_bf16 v[32:47], v[146:149], v[136:139], v[32:47]
	s_nop 10
	v_permlane32_swap_b32_e32 v0, v16
	v_permlane32_swap_b32_e32 v4, v20
	v_permlane32_swap_b32_e32 v8, v24
	v_permlane32_swap_b32_e32 v14, v30
	v_permlane32_swap_b32_e32 v48, v32
	v_permlane32_swap_b32_e32 v52, v36
	v_permlane32_swap_b32_e32 v53, v37
	v_permlane32_swap_b32_e32 v56, v40
	v_permlane32_swap_b32_e32 v57, v41
	v_permlane32_swap_b32_e32 v62, v46
	v_permlane32_swap_b32_e32 v63, v47
	v_mov_b32_e32 v152, v48
	v_mov_b32_e32 v153, v0
	v_permlane32_swap_b32_e32 v1, v17
	v_mov_b32_e32 v148, v20
	v_mov_b32_e32 v149, v36
	v_mov_b32_e32 v20, v37
	v_mov_b32_e32 v36, v56
	v_mov_b32_e32 v37, v8
	v_mov_b32_e32 v8, v57
	v_mov_b32_e32 v56, v46
	v_mov_b32_e32 v57, v30
	v_mov_b32_e32 v30, v47
	v_pk_fma_f32 v[46:47], v[172:173], v[164:165], v[152:153] op_sel:[0,1,0] op_sel_hi:[1,0,1]
	v_permlane32_swap_b32_e32 v49, v33
	v_mov_b32_e32 v48, v1
	v_pk_fma_f32 v[46:47], v[158:159], v[164:165], v[46:47]
	v_permlane32_swap_b32_e32 v2, v18
	v_permlane32_swap_b32_e32 v50, v34
	v_pk_fma_f32 v[48:49], v[174:175], v[46:47], v[48:49]
	v_mov_b32_e32 v146, v2
	v_mov_b32_e32 v147, v50
	v_pk_fma_f32 v[46:47], v[158:159], v[46:47], v[48:49] op_sel:[0,0,1] op_sel_hi:[1,1,0]
	v_permlane32_swap_b32_e32 v51, v35
	v_pk_fma_f32 v[48:49], v[142:143], v[46:47], v[146:147]
	v_permlane32_swap_b32_e32 v3, v19
	v_mov_b32_e32 v2, v51
	v_pk_fma_f32 v[46:47], v[158:159], v[46:47], v[48:49] op_sel:[0,0,1] op_sel_hi:[1,1,0]
	v_mov_b32_e32 v0, v32
	v_pk_fma_f32 v[2:3], v[160:161], v[46:47], v[2:3] op_sel:[0,1,0] op_sel_hi:[1,0,1]
	v_mov_b32_e32 v1, v16
	v_pk_fma_f32 v[2:3], v[158:159], v[46:47], v[2:3]
	v_mov_b32_e32 v16, v33
	v_pk_fma_f32 v[0:1], v[160:161], v[2:3], v[0:1] op_sel:[0,1,0] op_sel_hi:[1,0,1]
	v_mov_b32_e32 v32, v34
	v_pk_fma_f32 v[0:1], v[158:159], v[2:3], v[0:1]
	v_mov_b32_e32 v33, v18
; __device__ __forceinline__ void s5_phase(const Args& a, const Ctx& F) {
;     ...
; #pragma unroll
;         for (int i = 0; i < 32; ++i) {
;             const int r = (i & 3) + 4 * (i >> 3); const bool up = (i >> 2) & 1;
;             const float sr = up ? sre1[r] : sre0[r], si = up ? sim1[r] : sim0[r];
;             const float nre = __builtin_fmaf(lr, hre, __builtin_fmaf(nli, him, sr)), nim = __builtin_fmaf(lr, him, __builtin_fmaf(li, hre, si)); hre = nre; him = nim;
;         }
	v_pk_fma_f32 v[2:3], v[160:161], v[0:1], v[16:17] op_sel:[0,1,0] op_sel_hi:[1,0,1]
	v_mov_b32_e32 v18, v35
	v_pk_fma_f32 v[0:1], v[158:159], v[0:1], v[2:3]
	v_mov_b32_e32 v34, v52
	v_pk_fma_f32 v[2:3], v[160:161], v[0:1], v[32:33] op_sel:[0,1,0] op_sel_hi:[1,0,1]
	v_mov_b32_e32 v35, v4
	v_pk_fma_f32 v[0:1], v[158:159], v[0:1], v[2:3]
	v_permlane32_swap_b32_e32 v5, v21
	v_pk_fma_f32 v[2:3], v[160:161], v[0:1], v[18:19] op_sel:[0,1,0] op_sel_hi:[1,0,1]
	v_mov_b32_e32 v4, v53
	v_pk_fma_f32 v[0:1], v[158:159], v[0:1], v[2:3]
	v_permlane32_swap_b32_e32 v6, v22
	v_pk_fma_f32 v[2:3], v[160:161], v[0:1], v[34:35] op_sel:[0,1,0] op_sel_hi:[1,0,1]
	v_permlane32_swap_b32_e32 v54, v38
	v_pk_fma_f32 v[0:1], v[158:159], v[0:1], v[2:3]
	v_mov_b32_e32 v50, v54
	v_pk_fma_f32 v[2:3], v[160:161], v[0:1], v[4:5] op_sel:[0,1,0] op_sel_hi:[1,0,1]
	v_mov_b32_e32 v51, v6
	v_pk_fma_f32 v[0:1], v[158:159], v[0:1], v[2:3]
	v_permlane32_swap_b32_e32 v7, v23
	v_pk_fma_f32 v[2:3], v[160:161], v[0:1], v[50:51] op_sel:[0,1,0] op_sel_hi:[1,0,1]
	v_permlane32_swap_b32_e32 v55, v39
	v_mov_b32_e32 v54, v7
	v_pk_fma_f32 v[0:1], v[158:159], v[0:1], v[2:3]
	v_mov_b32_e32 v6, v38
	v_pk_fma_f32 v[2:3], v[142:143], v[0:1], v[54:55]
	v_mov_b32_e32 v7, v22
	v_pk_fma_f32 v[0:1], v[158:159], v[0:1], v[2:3] op_sel:[0,0,1] op_sel_hi:[1,1,0]
	v_mov_b32_e32 v22, v39
	v_pk_fma_f32 v[2:3], v[142:143], v[0:1], v[148:149]
	v_permlane32_swap_b32_e32 v9, v25
	v_pk_fma_f32 v[0:1], v[158:159], v[0:1], v[2:3] op_sel:[0,0,1] op_sel_hi:[1,1,0]
	v_permlane32_swap_b32_e32 v10, v26
	v_pk_fma_f32 v[2:3], v[160:161], v[0:1], v[20:21] op_sel:[0,1,0] op_sel_hi:[1,0,1]
	v_permlane32_swap_b32_e32 v58, v42
	v_pk_fma_f32 v[0:1], v[158:159], v[0:1], v[2:3]
	v_mov_b32_e32 v38, v40
	v_pk_fma_f32 v[2:3], v[160:161], v[0:1], v[6:7] op_sel:[0,1,0] op_sel_hi:[1,0,1]
	v_mov_b32_e32 v39, v24
	v_pk_fma_f32 v[0:1], v[158:159], v[0:1], v[2:3]
	v_mov_b32_e32 v40, v25
	v_pk_fma_f32 v[2:3], v[160:161], v[0:1], v[22:23] op_sel:[0,1,0] op_sel_hi:[1,0,1]
	v_mov_b32_e32 v24, v58
	v_pk_fma_f32 v[0:1], v[158:159], v[0:1], v[2:3]
	v_mov_b32_e32 v25, v10
	v_pk_fma_f32 v[2:3], v[160:161], v[0:1], v[36:37] op_sel:[0,1,0] op_sel_hi:[1,0,1]
	v_permlane32_swap_b32_e32 v59, v43
	v_pk_fma_f32 v[0:1], v[158:159], v[0:1], v[2:3]
	v_permlane32_swap_b32_e32 v11, v27
	v_pk_fma_f32 v[2:3], v[160:161], v[0:1], v[8:9] op_sel:[0,1,0] op_sel_hi:[1,0,1]
	v_mov_b32_e32 v10, v59
	v_pk_fma_f32 v[0:1], v[158:159], v[0:1], v[2:3]
	v_mov_b32_e32 v150, v26
	v_pk_fma_f32 v[2:3], v[160:161], v[0:1], v[24:25] op_sel:[0,1,0] op_sel_hi:[1,0,1]
	v_mov_b32_e32 v151, v42
	v_pk_fma_f32 v[0:1], v[158:159], v[0:1], v[2:3]
	v_mov_b32_e32 v26, v43
	v_pk_fma_f32 v[2:3], v[160:161], v[0:1], v[10:11] op_sel:[0,1,0] op_sel_hi:[1,0,1]
	v_permlane32_swap_b32_e32 v12, v28
	v_pk_fma_f32 v[0:1], v[158:159], v[0:1], v[2:3]
	v_permlane32_swap_b32_e32 v60, v44
	v_pk_fma_f32 v[2:3], v[160:161], v[0:1], v[38:39] op_sel:[0,1,0] op_sel_hi:[1,0,1]
	v_mov_b32_e32 v42, v60
	v_pk_fma_f32 v[0:1], v[158:159], v[0:1], v[2:3]
	v_mov_b32_e32 v43, v12
	v_pk_fma_f32 v[2:3], v[142:143], v[0:1], v[40:41]
	v_permlane32_swap_b32_e32 v61, v45
	v_pk_fma_f32 v[0:1], v[158:159], v[0:1], v[2:3] op_sel:[0,0,1] op_sel_hi:[1,1,0]
	v_permlane32_swap_b32_e32 v13, v29
	v_pk_fma_f32 v[2:3], v[142:143], v[0:1], v[150:151]
	v_mov_b32_e32 v12, v61
	v_pk_fma_f32 v[0:1], v[158:159], v[0:1], v[2:3] op_sel:[0,0,1] op_sel_hi:[1,1,0]
	v_mov_b32_e32 v52, v44
	v_pk_fma_f32 v[2:3], v[160:161], v[0:1], v[26:27] op_sel:[0,1,0] op_sel_hi:[1,0,1]
	v_mov_b32_e32 v53, v28
	v_pk_fma_f32 v[0:1], v[158:159], v[0:1], v[2:3]
	v_mov_b32_e32 v28, v45
	v_pk_fma_f32 v[2:3], v[160:161], v[0:1], v[42:43] op_sel:[0,1,0] op_sel_hi:[1,0,1]
	v_mov_b32_e32 v44, v62
	v_pk_fma_f32 v[0:1], v[158:159], v[0:1], v[2:3]
	v_mov_b32_e32 v45, v14
	v_pk_fma_f32 v[2:3], v[160:161], v[0:1], v[12:13] op_sel:[0,1,0] op_sel_hi:[1,0,1]
	v_permlane32_swap_b32_e32 v15, v31
	v_pk_fma_f32 v[0:1], v[158:159], v[0:1], v[2:3]
	v_mov_b32_e32 v14, v63
	v_pk_fma_f32 v[2:3], v[160:161], v[0:1], v[44:45] op_sel:[0,1,0] op_sel_hi:[1,0,1]
	s_nop 0
	v_pk_fma_f32 v[0:1], v[158:159], v[0:1], v[2:3]
	s_nop 0
	v_pk_fma_f32 v[2:3], v[160:161], v[0:1], v[14:15] op_sel:[0,1,0] op_sel_hi:[1,0,1]
	s_nop 0
	v_pk_fma_f32 v[0:1], v[158:159], v[0:1], v[2:3]
	s_nop 0
	v_pk_fma_f32 v[2:3], v[160:161], v[0:1], v[52:53] op_sel:[0,1,0] op_sel_hi:[1,0,1]
	s_nop 0
	v_pk_fma_f32 v[0:1], v[158:159], v[0:1], v[2:3]
	s_nop 0
	v_pk_fma_f32 v[2:3], v[160:161], v[0:1], v[28:29] op_sel:[0,1,0] op_sel_hi:[1,0,1]
	s_nop 0
	v_pk_fma_f32 v[0:1], v[158:159], v[0:1], v[2:3]
	s_nop 0
	v_pk_fma_f32 v[2:3], v[160:161], v[0:1], v[56:57] op_sel:[0,1,0] op_sel_hi:[1,0,1]
	s_nop 0
	v_pk_fma_f32 v[0:1], v[158:159], v[0:1], v[2:3]
	s_nop 0
	v_pk_fma_f32 v[2:3], v[160:161], v[0:1], v[30:31] op_sel:[0,1,0] op_sel_hi:[1,0,1]
	s_nop 0
	v_pk_fma_f32 v[164:165], v[158:159], v[0:1], v[2:3]
	s_cbranch_scc0 .LBB0_377
; #define LAS __attribute__((address_space(3)))
; template <bool REV> ...
;     constexpr int SG = REV ? -1 : 1;
;     constexpr int TSTEP = SG * 64 * 16, CSTEP16 = SG * 32 * 16, SSTEP = SG * 16;
;     const float nli = -li;
;     const int nl = lane & 31, hl = lane >> 5, tk = lane & 15, kq = lane >> 4;
;     const bf16* pA = U + gbase + SG * (2 * nl + hl) * 16;
;     const bf16* pB = U + gbase + SG * (2 * tk + (kq >> 1)) * 16 + 8 * (kq & 1);
;     const bf16* pU = U + gbase + SG * (2 * tk) * 16 + 4 * kq;
;     bf16* pY = YA + gbase + SG * (2 * tk) * 16 + 4 * kq;
;     bf16x8 A0 = *(const bf16x8*)pA, A1 = *(const bf16x8*)(pA + 8);
;     bf16x8 Ub[2]; Ub[0] = *(const bf16x8*)pB; Ub[1] = *(const bf16x8*)(pB + CSTEP16);
;     u32x2 pv[2][2], uv[2][2];
; #pragma unroll
;     for (int th = 0; th < 2; ++th)
; #pragma unroll
;         for (int sx = 0; sx < 2; ++sx) { pv[th][sx] = (u32x2){0u, 0u}; uv[th][sx] = (u32x2){0u, 0u}; }
;     const f32x2 dsk01 = (f32x2){dsk[0], dsk[1]}, dsk23 = (f32x2){dsk[2], dsk[3]};
;     LAS unsigned* wbase = (LAS unsigned*)(my + ((lane & 3) << 2));
; __device__ __forceinline__ void s5_phase(const Args& a, const Ctx& F) {
;     ...
;     const size_t gbase = ((size_t)(b * NG + g) * SEQ + (d ? SEQ - 1 : 0)) * 16;
;     unsigned char* Y8 = ws + WS_YA8;
;     if (d) s5_latent<true>(U, YA, Y8, gbase, Bf, Cf, Kf, lr, li, hre, him, my, dsk, lane);
;     else s5_latent<false>(U, YA, Y8, gbase, Bf, Cf, Kf, lr, li, hre, him, my, dsk, lane);
	s_add_u32 s6, s30, 0x4c400000
	s_addc_u32 s7, s31, 0
	s_lshl_b32 s19, s42, 9
	s_or_b32 s10, s35, s19
	s_ashr_i32 s11, s10, 31
	s_and_b64 s[0:1], s[0:1], exec
	s_cselect_b32 s0, 0, 0x1fff0
	s_add_u32 s8, s30, 0x70400000
	s_addc_u32 s9, s31, 0
	s_lshl_b32 s1, s95, 13
	s_add_i32 s35, s1, 0
	s_lshl_b32 s23, s0, 1
	s_lshl_b64 s[0:1], s[10:11], 18
	s_or_b32 s0, s0, s23
	s_add_u32 s0, s30, s0
	v_ashrrev_i32_e32 v207, 4, v140
	s_addc_u32 s1, s31, s1
	v_lshlrev_b32_e32 v0, 3, v207
	s_add_u32 s10, s0, 0x2bc00000
	v_and_b32_e32 v206, 15, v140
	v_and_b32_e32 v0, 8, v0
	s_mov_b64 s[16:17], 0x4c400000
	s_mov_b32 s52, 0
	s_addc_u32 s11, s1, 0
	v_mov_b32_e32 v163, 0
	s_and_b64 vcc, exec, s[12:13]
	v_lshlrev_b32_e32 v170, 4, v141
	v_lshlrev_b32_e32 v162, 1, v0
	v_lshlrev_b32_e32 v166, 2, v207
	v_lshlrev_b32_e32 v213, 2, v140
	v_and_b32_e32 v212, -4, v140
	v_lshl_add_u32 v205, v206, 8, s35
	v_lshrrev_b32_e32 v208, 1, v206
	v_bitop3_b32 v214, v140, 4, -4 bitop3:0x6c
	v_bitop3_b32 v215, v140, 8, -4 bitop3:0x6c
	v_bitop3_b32 v216, v140, 12, -4 bitop3:0x6c
	v_bitop3_b32 v217, v140, 16, -4 bitop3:0x6c
	v_bitop3_b32 v218, v140, 20, -4 bitop3:0x6c
	v_bitop3_b32 v219, v140, 24, -4 bitop3:0x6c
	v_bitop3_b32 v220, v140, 28, -4 bitop3:0x6c
	v_bitop3_b32 v221, v140, 32, -4 bitop3:0x6c
	v_bitop3_b32 v222, v140, 36, -4 bitop3:0x6c
	v_bitop3_b32 v223, v140, 40, -4 bitop3:0x6c
	v_bitop3_b32 v224, v140, 44, -4 bitop3:0x6c
	v_bitop3_b32 v225, v140, 48, -4 bitop3:0x6c
	v_bitop3_b32 v226, v140, 52, -4 bitop3:0x6c
	v_bitop3_b32 v227, v140, 56, -4 bitop3:0x6c
	v_bitop3_b32 v228, v140, 60, -4 bitop3:0x6c
	v_add_u32_e32 v211, 4, v207
	v_add_u32_e32 v210, 8, v207
	v_add_u32_e32 v209, 12, v207
	v_and_b32_e32 v168, 16, v140
	s_cbranch_vccz .LBB0_399
	v_mul_i32_i24_e32 v4, -2, v206
	v_sub_u32_e32 v4, v4, v204
	v_sub_u32_e32 v0, 0, v170
	v_lshlrev_b32_e32 v4, 4, v4
	v_ashrrev_i32_e32 v1, 31, v0
	v_ashrrev_i32_e32 v5, 31, v4
	v_lshlrev_b64 v[0:1], 1, v[0:1]
	v_lshlrev_b64 v[4:5], 1, v[4:5]
	v_lshl_add_u64 v[2:3], s[10:11], 0, v[0:1]
	v_lshl_add_u64 v[6:7], s[10:11], 0, v[4:5]
	v_lshl_add_u64 v[6:7], v[6:7], 0, v[162:163]
	global_load_dwordx4 v[152:155], v[2:3], off
	global_load_dwordx4 v[148:151], v[2:3], off offset:16
	global_load_dwordx4 v[144:147], v[6:7], off
	global_load_dwordx4 v[140:143], v[6:7], off offset:-1024
	s_add_i32 s0, s19, s33
	s_add_i32 s0, s0, s34
	s_ashr_i32 s1, s0, 31
	s_lshl_b64 s[0:1], s[0:1], 18
	s_or_b32 s0, s0, s23
	s_add_u32 s12, s30, s0
	s_addc_u32 s13, s31, s1
	v_mov_b32_e32 v169, v163
	v_mul_i32_i24_e32 v8, 0xffffffe0, v206
	v_and_b32_e32 v2, 12, v213
	v_lshl_add_u64 v[194:195], s[12:13], 0, v[0:1]
	v_lshl_add_u64 v[0:1], s[0:1], 0, v[168:169]
	v_ashrrev_i32_e32 v9, 31, v8
	v_add_u32_e32 v2, s35, v2
	v_lshl_add_u64 v[0:1], v[0:1], 0, v[4:5]
	v_ashrrev_i32_e32 v167, 31, v166
	v_lshl_add_u32 v248, v212, 2, v2
	v_lshl_add_u32 v247, v214, 2, v2
	v_lshl_add_u32 v246, v215, 2, v2
	v_lshl_add_u32 v245, v216, 2, v2
	v_lshl_add_u32 v244, v217, 2, v2
	v_lshl_add_u32 v243, v218, 2, v2
	v_lshl_add_u32 v242, v219, 2, v2
	v_lshl_add_u32 v241, v220, 2, v2
	v_lshl_add_u32 v240, v221, 2, v2
	v_lshl_add_u32 v239, v222, 2, v2
	v_lshl_add_u32 v238, v223, 2, v2
	v_lshl_add_u32 v237, v224, 2, v2
	v_lshl_add_u32 v232, v225, 2, v2
	v_lshl_add_u32 v231, v226, 2, v2
	v_lshl_add_u32 v230, v227, 2, v2
	v_lshl_add_u32 v229, v228, 2, v2
	v_xor_b32_e32 v2, v208, v207
	v_xor_b32_e32 v3, v211, v208
	v_xor_b32_e32 v6, v210, v208
	v_xor_b32_e32 v7, v209, v208
	v_bitop3_b32 v10, v208, v207, 8 bitop3:0x36
	v_bitop3_b32 v11, v208, v211, 8 bitop3:0x36
	v_bitop3_b32 v12, v208, v210, 8 bitop3:0x36
	v_bitop3_b32 v13, v208, v209, 8 bitop3:0x36
	v_lshl_add_u64 v[196:197], s[30:31], 0, v[0:1]
	v_lshl_add_u64 v[0:1], v[8:9], 1, s[0:1]
	v_lshlrev_b32_e32 v2, 4, v2
	v_lshlrev_b32_e32 v3, 4, v3
	v_lshlrev_b32_e32 v6, 4, v6
	v_lshlrev_b32_e32 v7, 4, v7
	v_lshlrev_b32_e32 v10, 4, v10
	v_lshlrev_b32_e32 v11, 4, v11
	v_lshlrev_b32_e32 v12, 4, v12
	v_lshlrev_b32_e32 v13, 4, v13
	v_lshl_add_u64 v[0:1], v[166:167], 1, v[0:1]
	v_mov_b32_e32 v176, v163
	v_mov_b32_e32 v177, v163
	s_sub_u32 s76, 0x10000000, s30
	s_add_u32 s78, s30, 0x1bc00000
	s_addc_u32 s79, s31, 0
	s_add_u32 s80, s30, 0x3c3ff000
	s_addc_u32 s81, s31, 0
	s_add_u32 s82, s30, 0x1bbff000
	s_addc_u32 s83, s31, 0
	v_lshl_add_u64 v[184:185], s[30:31], 0, v[0:1]
	s_mov_b64 s[12:13], 0
	s_mov_b32 s53, 0x2bbff000
	s_mov_b32 s18, 0x3dd2d3e8
	s_mov_b32 s22, 0xc0135761
	v_mov_b32_e32 v254, s22
	s_movk_i32 s54, 0x80
	s_mov_b32 s55, 0x7050301
	s_mov_b64 s[38:39], 0x4c3fffe0
	s_mov_b64 s[40:41], 0x4c3ffc00
	s_mov_b64 s[42:43], 0x4c3ffbe0
	v_add_u32_e32 v235, v205, v2
	v_add_u32_e32 v236, v205, v3
	v_add_u32_e32 v234, v205, v6
	v_add_u32_e32 v233, v205, v7
	v_add_u32_e32 v169, v205, v10
	v_add_u32_e32 v171, v205, v11
	v_add_u32_e32 v163, v205, v12
	v_add_u32_e32 v167, v205, v13
	v_mov_b64_e32 v[180:181], v[176:177]
	v_mov_b64_e32 v[188:189], v[176:177]
	v_mov_b64_e32 v[192:193], v[176:177]
	v_mov_b64_e32 v[178:179], v[176:177]
	v_mov_b64_e32 v[182:183], v[176:177]
	v_mov_b64_e32 v[186:187], v[176:177]
	v_mov_b64_e32 v[190:191], v[176:177]
	v_mov_b32_e32 v202, v165
	v_mov_b32_e32 v203, v164
	s_waitcnt vmcnt(0)
	s_branch .LBB0_381

; __device__ __forceinline__ unsigned cvt_pk_bf16(float lo, float hi) { unsigned r; asm volatile("v_cvt_pk_bf16_f32 %0, %1, %2" : "=v"(r) : "v"(lo), "v"(hi)); return r; }
; __device__ __forceinline__ float bf_lo(unsigned w) { return __uint_as_float(w << 16); }
; __device__ __forceinline__ float bf_hi(unsigned w) { return __uint_as_float(w & 0xffff0000u); }
; __device__ __forceinline__ f32x2 gelu2(f32x2 v) {
;     const f32x2 t = v * v, w = t * (-0.10294324f) + (-2.3022082f), a = v * w;
;     f32x2 e; e.x = __builtin_amdgcn_exp2f(a.x); e.y = __builtin_amdgcn_exp2f(a.y);
;     const f32x2 q = e + 1.0f; f32x2 r; r.x = __builtin_amdgcn_rcpf(q.x); r.y = __builtin_amdgcn_rcpf(q.y);
;     return v * r;
; }
; template <bool REV> ...
;     ...
;                 else { const u32x2 p = pv[th][sx], u = uv[th][sx];
;                     const f32x2 v01 = (f32x2){y[0], y[1]} + (f32x2){bf_lo(p.x), bf_hi(p.x)} + dsk01 * (f32x2){bf_lo(u.x), bf_hi(u.x)};
;                     const f32x2 v23 = (f32x2){y[2], y[3]} + (f32x2){bf_lo(p.y), bf_hi(p.y)} + dsk23 * (f32x2){bf_lo(u.y), bf_hi(u.y)};
;                     const f32x2 o01 = gelu2(v01), o23 = gelu2(v23);
;                     u32x2 w; w.x = cvt_pk_bf16(o01.x, o01.y); w.y = cvt_pk_bf16(o23.x, o23.y); *(u32x2*)yo = w;
;                     { const unsigned x8 = pack_i8x4(o01.x, o01.y, o23.x, o23.y, 1.0f / YA8_R);
;                       *(unsigned*)(Y8 + (yo - YA)) = x8; }
;                     pv[th][sx] = *(const u32x2*)(yo + adv); uv[th][sx] = *(const u32x2*)(pU + th * CSTEP16 + sx * SSTEP + adv); }
.LBB0_385:
	s_andn2_b64 vcc, exec, s[0:1]
	s_cbranch_vccnz .LBB0_387
	v_lshlrev_b32_e32 v24, 16, v192
	v_and_b32_e32 v25, 0xffff0000, v192
	s_nop 2
	v_pk_add_f32 v[20:21], v[20:21], v[24:25]
	v_lshlrev_b32_e32 v24, 16, v190
	v_and_b32_e32 v25, 0xffff0000, v190
	v_pk_fma_f32 v[20:21], v[64:65], v[24:25], v[20:21]
	v_lshlrev_b32_e32 v24, 16, v193
	v_and_b32_e32 v25, 0xffff0000, v193
	v_pk_add_f32 v[22:23], v[22:23], v[24:25]
	v_lshlrev_b32_e32 v24, 16, v191
	v_and_b32_e32 v25, 0xffff0000, v191
	v_pk_fma_f32 v[22:23], v[66:67], v[24:25], v[22:23]
	v_pk_mul_f32 v[24:25], v[20:21], v[20:21]
	v_pk_fma_f32 v[24:25], v[24:25], s[18:19], v[254:255] op_sel_hi:[1,0,0] neg_lo:[1,0,0] neg_hi:[1,0,0]
	v_pk_mul_f32 v[28:29], v[22:23], v[22:23]
	v_pk_mul_f32 v[24:25], v[20:21], v[24:25]
	v_pk_fma_f32 v[26:27], v[28:29], s[18:19], v[254:255] op_sel_hi:[1,0,0] neg_lo:[1,0,0] neg_hi:[1,0,0]
	v_exp_f32_e32 v24, v24
	v_exp_f32_e32 v25, v25
	v_pk_mul_f32 v[26:27], v[22:23], v[26:27]
	v_pk_add_f32 v[24:25], v[24:25], 1.0 op_sel_hi:[1,0]
	v_exp_f32_e32 v26, v26
	v_exp_f32_e32 v27, v27
	v_rcp_f32_e32 v24, v24
	v_rcp_f32_e32 v25, v25
	v_pk_add_f32 v[26:27], v[26:27], 1.0 op_sel_hi:[1,0]
	s_nop 0
	v_rcp_f32_e32 v26, v26
	v_rcp_f32_e32 v27, v27
	v_pk_mul_f32 v[20:21], v[20:21], v[24:25]
	v_pk_mul_f32 v[22:23], v[22:23], v[26:27]
	v_cvt_pk_bf16_f32 v24, v20, v21
	v_mul_f32_e32 v14, 0x3d924925, v20
	v_mul_f32_e32 v20, 0x3d924925, v21
	v_cvt_pknorm_i16_f32 v14, v14, v20
	v_mul_f32_e32 v20, 0x3d924925, v22
	v_mul_f32_e32 v21, 0x3d924925, v23
	v_cvt_pknorm_i16_f32 v20, v20, v21
	v_pk_add_i16 v14, v14, s54 op_sel_hi:[1,0] clamp
	v_pk_add_i16 v20, v20, s54 op_sel_hi:[1,0] clamp
	v_mov_b32_e32 v21, s7
	v_perm_b32 v14, v20, v14, s55
	v_subrev_u32_e32 v20, s6, v200
	v_cvt_pk_bf16_f32 v25, v22, v23
	global_store_dwordx2 v[200:201], v[24:25], off
	v_lshrrev_b32_e32 v20, 1, v20
	global_store_dword v20, v14, s[8:9]
	global_load_dwordx2 v[192:193], v253, s[80:81] offset:2048
	global_load_dwordx2 v[190:191], v253, s[82:83] offset:2048

; __device__ __forceinline__ unsigned cvt_pk_bf16(float lo, float hi) { unsigned r; asm volatile("v_cvt_pk_bf16_f32 %0, %1, %2" : "=v"(r) : "v"(lo), "v"(hi)); return r; }
; __device__ __forceinline__ float bf_lo(unsigned w) { return __uint_as_float(w << 16); }
; __device__ __forceinline__ float bf_hi(unsigned w) { return __uint_as_float(w & 0xffff0000u); }
; __device__ __forceinline__ f32x2 gelu2(f32x2 v) {
;     const f32x2 t = v * v, w = t * (-0.10294324f) + (-2.3022082f), a = v * w;
;     f32x2 e; e.x = __builtin_amdgcn_exp2f(a.x); e.y = __builtin_amdgcn_exp2f(a.y);
;     const f32x2 q = e + 1.0f; f32x2 r; r.x = __builtin_amdgcn_rcpf(q.x); r.y = __builtin_amdgcn_rcpf(q.y);
;     return v * r;
; }
; template <bool REV> ...
;     ...
;                 else { const u32x2 p = pv[th][sx], u = uv[th][sx];
;                     const f32x2 v01 = (f32x2){y[0], y[1]} + (f32x2){bf_lo(p.x), bf_hi(p.x)} + dsk01 * (f32x2){bf_lo(u.x), bf_hi(u.x)};
;                     const f32x2 v23 = (f32x2){y[2], y[3]} + (f32x2){bf_lo(p.y), bf_hi(p.y)} + dsk23 * (f32x2){bf_lo(u.y), bf_hi(u.y)};
;                     const f32x2 o01 = gelu2(v01), o23 = gelu2(v23);
;                     u32x2 w; w.x = cvt_pk_bf16(o01.x, o01.y); w.y = cvt_pk_bf16(o23.x, o23.y); *(u32x2*)yo = w;
;                     { const unsigned x8 = pack_i8x4(o01.x, o01.y, o23.x, o23.y, 1.0f / YA8_R);
;                       *(unsigned*)(Y8 + (yo - YA)) = x8; }
;                     pv[th][sx] = *(const u32x2*)(yo + adv); uv[th][sx] = *(const u32x2*)(pU + th * CSTEP16 + sx * SSTEP + adv); }
.LBB0_389:
	s_andn2_b64 vcc, exec, s[50:51]
	s_cbranch_vccnz .LBB0_391
	v_lshlrev_b32_e32 v4, 16, v188
	v_and_b32_e32 v5, 0xffff0000, v188
	s_nop 2
	v_pk_add_f32 v[0:1], v[0:1], v[4:5]
	v_lshlrev_b32_e32 v4, 16, v186
	v_and_b32_e32 v5, 0xffff0000, v186
	v_pk_fma_f32 v[0:1], v[64:65], v[4:5], v[0:1]
	v_lshlrev_b32_e32 v4, 16, v189
	v_and_b32_e32 v5, 0xffff0000, v189
	v_pk_add_f32 v[2:3], v[2:3], v[4:5]
	v_lshlrev_b32_e32 v4, 16, v187
	v_and_b32_e32 v5, 0xffff0000, v187
	v_pk_fma_f32 v[2:3], v[66:67], v[4:5], v[2:3]
	v_pk_mul_f32 v[4:5], v[0:1], v[0:1]
	v_pk_fma_f32 v[4:5], v[4:5], s[18:19], v[254:255] op_sel_hi:[1,0,0] neg_lo:[1,0,0] neg_hi:[1,0,0]
	v_pk_mul_f32 v[10:11], v[2:3], v[2:3]
	v_pk_mul_f32 v[4:5], v[0:1], v[4:5]
	v_pk_fma_f32 v[6:7], v[10:11], s[18:19], v[254:255] op_sel_hi:[1,0,0] neg_lo:[1,0,0] neg_hi:[1,0,0]
	v_exp_f32_e32 v4, v4
	v_exp_f32_e32 v5, v5
	v_pk_mul_f32 v[6:7], v[2:3], v[6:7]
	v_pk_add_f32 v[4:5], v[4:5], 1.0 op_sel_hi:[1,0]
	v_exp_f32_e32 v6, v6
	v_exp_f32_e32 v7, v7
	v_rcp_f32_e32 v4, v4
	v_rcp_f32_e32 v5, v5
	v_pk_add_f32 v[6:7], v[6:7], 1.0 op_sel_hi:[1,0]
	s_nop 0
	v_rcp_f32_e32 v6, v6
	v_rcp_f32_e32 v7, v7
	v_pk_mul_f32 v[0:1], v[0:1], v[4:5]
	v_pk_mul_f32 v[2:3], v[2:3], v[6:7]
	v_cvt_pk_bf16_f32 v4, v0, v1
	v_mul_f32_e32 v0, 0x3d924925, v0
	v_mul_f32_e32 v1, 0x3d924925, v1
	v_cvt_pk_bf16_f32 v5, v2, v3
	v_cvt_pknorm_i16_f32 v0, v0, v1
	v_mul_f32_e32 v1, 0x3d924925, v2
	v_mul_f32_e32 v2, 0x3d924925, v3
	v_cvt_pknorm_i16_f32 v1, v1, v2
	v_pk_add_i16 v0, v0, s54 op_sel_hi:[1,0] clamp
	v_pk_add_i16 v1, v1, s54 op_sel_hi:[1,0] clamp
	global_store_dwordx2 v[8:9], v[4:5], off
	v_perm_b32 v2, v1, v0, s55
	v_subrev_u32_e32 v0, s6, v8
	v_lshrrev_b32_e32 v0, 1, v0
	global_store_dword v0, v2, s[8:9]
	global_load_dwordx2 v[188:189], v253, s[80:81] offset:2016
	global_load_dwordx2 v[186:187], v253, s[82:83] offset:2016

; __device__ __forceinline__ unsigned cvt_pk_bf16(float lo, float hi) { unsigned r; asm volatile("v_cvt_pk_bf16_f32 %0, %1, %2" : "=v"(r) : "v"(lo), "v"(hi)); return r; }
; __device__ __forceinline__ float bf_lo(unsigned w) { return __uint_as_float(w << 16); }
; __device__ __forceinline__ float bf_hi(unsigned w) { return __uint_as_float(w & 0xffff0000u); }
; __device__ __forceinline__ f32x2 gelu2(f32x2 v) {
;     const f32x2 t = v * v, w = t * (-0.10294324f) + (-2.3022082f), a = v * w;
;     f32x2 e; e.x = __builtin_amdgcn_exp2f(a.x); e.y = __builtin_amdgcn_exp2f(a.y);
;     const f32x2 q = e + 1.0f; f32x2 r; r.x = __builtin_amdgcn_rcpf(q.x); r.y = __builtin_amdgcn_rcpf(q.y);
;     return v * r;
; }
; template <bool REV> ...
;     ...
;                 else { const u32x2 p = pv[th][sx], u = uv[th][sx];
;                     const f32x2 v01 = (f32x2){y[0], y[1]} + (f32x2){bf_lo(p.x), bf_hi(p.x)} + dsk01 * (f32x2){bf_lo(u.x), bf_hi(u.x)};
;                     const f32x2 v23 = (f32x2){y[2], y[3]} + (f32x2){bf_lo(p.y), bf_hi(p.y)} + dsk23 * (f32x2){bf_lo(u.y), bf_hi(u.y)};
;                     const f32x2 o01 = gelu2(v01), o23 = gelu2(v23);
;                     u32x2 w; w.x = cvt_pk_bf16(o01.x, o01.y); w.y = cvt_pk_bf16(o23.x, o23.y); *(u32x2*)yo = w;
;                     { const unsigned x8 = pack_i8x4(o01.x, o01.y, o23.x, o23.y, 1.0f / YA8_R);
;                       *(unsigned*)(Y8 + (yo - YA)) = x8; }
;                     pv[th][sx] = *(const u32x2*)(yo + adv); uv[th][sx] = *(const u32x2*)(pU + th * CSTEP16 + sx * SSTEP + adv); }
.LBB0_393:
	s_andn2_b64 vcc, exec, s[46:47]
	s_cbranch_vccnz .LBB0_395
	v_lshlrev_b32_e32 v28, 16, v180
	v_and_b32_e32 v29, 0xffff0000, v180
	s_nop 2
	v_pk_add_f32 v[20:21], v[20:21], v[28:29]
	v_lshlrev_b32_e32 v28, 16, v182
	v_and_b32_e32 v29, 0xffff0000, v182
	v_pk_fma_f32 v[20:21], v[64:65], v[28:29], v[20:21]
	v_lshlrev_b32_e32 v28, 16, v181
	v_and_b32_e32 v29, 0xffff0000, v181
	v_pk_add_f32 v[22:23], v[22:23], v[28:29]
	v_lshlrev_b32_e32 v28, 16, v183
	v_and_b32_e32 v29, 0xffff0000, v183
	v_pk_fma_f32 v[22:23], v[66:67], v[28:29], v[22:23]
	v_pk_mul_f32 v[28:29], v[20:21], v[20:21]
	v_pk_fma_f32 v[28:29], v[28:29], s[18:19], v[254:255] op_sel_hi:[1,0,0] neg_lo:[1,0,0] neg_hi:[1,0,0]
	v_pk_mul_f32 v[34:35], v[22:23], v[22:23]
	v_pk_mul_f32 v[28:29], v[20:21], v[28:29]
	v_pk_fma_f32 v[32:33], v[34:35], s[18:19], v[254:255] op_sel_hi:[1,0,0] neg_lo:[1,0,0] neg_hi:[1,0,0]
	v_exp_f32_e32 v28, v28
	v_exp_f32_e32 v29, v29
	v_pk_mul_f32 v[32:33], v[22:23], v[32:33]
	v_pk_add_f32 v[28:29], v[28:29], 1.0 op_sel_hi:[1,0]
	v_exp_f32_e32 v32, v32
	v_exp_f32_e32 v33, v33
	v_rcp_f32_e32 v28, v28
	v_rcp_f32_e32 v29, v29
	v_pk_add_f32 v[32:33], v[32:33], 1.0 op_sel_hi:[1,0]
	s_nop 0
	v_rcp_f32_e32 v32, v32
	v_rcp_f32_e32 v33, v33
	v_pk_mul_f32 v[20:21], v[20:21], v[28:29]
	v_pk_mul_f32 v[22:23], v[22:23], v[32:33]
	v_cvt_pk_bf16_f32 v28, v20, v21
	v_mul_f32_e32 v14, 0x3d924925, v20
	v_mul_f32_e32 v20, 0x3d924925, v21
	v_cvt_pknorm_i16_f32 v14, v14, v20
	v_mul_f32_e32 v20, 0x3d924925, v22
	v_mul_f32_e32 v21, 0x3d924925, v23
	v_cvt_pknorm_i16_f32 v20, v20, v21
	v_pk_add_i16 v14, v14, s54 op_sel_hi:[1,0] clamp
	v_pk_add_i16 v20, v20, s54 op_sel_hi:[1,0] clamp
	v_mov_b32_e32 v21, s7
	v_perm_b32 v14, v20, v14, s55
	v_subrev_u32_e32 v20, s6, v26
	v_cvt_pk_bf16_f32 v29, v22, v23
	global_store_dwordx2 v[26:27], v[28:29], off
	v_lshrrev_b32_e32 v20, 1, v20
	global_store_dword v20, v14, s[8:9]
	global_load_dwordx2 v[180:181], v253, s[80:81] offset:1024
	global_load_dwordx2 v[182:183], v253, s[82:83] offset:1024

; __device__ __forceinline__ unsigned cvt_pk_bf16(float lo, float hi) { unsigned r; asm volatile("v_cvt_pk_bf16_f32 %0, %1, %2" : "=v"(r) : "v"(lo), "v"(hi)); return r; }
; __device__ __forceinline__ float bf_lo(unsigned w) { return __uint_as_float(w << 16); }
; __device__ __forceinline__ float bf_hi(unsigned w) { return __uint_as_float(w & 0xffff0000u); }
; __device__ __forceinline__ f32x2 gelu2(f32x2 v) {
;     const f32x2 t = v * v, w = t * (-0.10294324f) + (-2.3022082f), a = v * w;
;     f32x2 e; e.x = __builtin_amdgcn_exp2f(a.x); e.y = __builtin_amdgcn_exp2f(a.y);
;     const f32x2 q = e + 1.0f; f32x2 r; r.x = __builtin_amdgcn_rcpf(q.x); r.y = __builtin_amdgcn_rcpf(q.y);
;     return v * r;
; }
; template <bool REV> ...
;     ...
;                 else { const u32x2 p = pv[th][sx], u = uv[th][sx];
;                     const f32x2 v01 = (f32x2){y[0], y[1]} + (f32x2){bf_lo(p.x), bf_hi(p.x)} + dsk01 * (f32x2){bf_lo(u.x), bf_hi(u.x)};
;                     const f32x2 v23 = (f32x2){y[2], y[3]} + (f32x2){bf_lo(p.y), bf_hi(p.y)} + dsk23 * (f32x2){bf_lo(u.y), bf_hi(u.y)};
;                     const f32x2 o01 = gelu2(v01), o23 = gelu2(v23);
;                     u32x2 w; w.x = cvt_pk_bf16(o01.x, o01.y); w.y = cvt_pk_bf16(o23.x, o23.y); *(u32x2*)yo = w;
;                     { const unsigned x8 = pack_i8x4(o01.x, o01.y, o23.x, o23.y, 1.0f / YA8_R);
;                       *(unsigned*)(Y8 + (yo - YA)) = x8; }
;                     pv[th][sx] = *(const u32x2*)(yo + adv); uv[th][sx] = *(const u32x2*)(pU + th * CSTEP16 + sx * SSTEP + adv); }
.LBB0_397:
	s_andn2_b64 vcc, exec, s[46:47]
	s_cbranch_vccnz .LBB0_380
	v_lshlrev_b32_e32 v4, 16, v176
	v_and_b32_e32 v5, 0xffff0000, v176
	s_nop 2
	v_pk_add_f32 v[0:1], v[0:1], v[4:5]
	v_lshlrev_b32_e32 v4, 16, v178
	v_and_b32_e32 v5, 0xffff0000, v178
	v_pk_fma_f32 v[0:1], v[64:65], v[4:5], v[0:1]
	v_lshlrev_b32_e32 v4, 16, v177
	v_and_b32_e32 v5, 0xffff0000, v177
	v_pk_add_f32 v[2:3], v[2:3], v[4:5]
	v_lshlrev_b32_e32 v4, 16, v179
	v_and_b32_e32 v5, 0xffff0000, v179
	v_pk_fma_f32 v[2:3], v[66:67], v[4:5], v[2:3]
	v_pk_mul_f32 v[4:5], v[0:1], v[0:1]
	v_pk_fma_f32 v[4:5], v[4:5], s[18:19], v[254:255] op_sel_hi:[1,0,0] neg_lo:[1,0,0] neg_hi:[1,0,0]
	v_pk_mul_f32 v[10:11], v[2:3], v[2:3]
	v_pk_mul_f32 v[4:5], v[0:1], v[4:5]
	v_pk_fma_f32 v[6:7], v[10:11], s[18:19], v[254:255] op_sel_hi:[1,0,0] neg_lo:[1,0,0] neg_hi:[1,0,0]
	v_exp_f32_e32 v4, v4
	v_exp_f32_e32 v5, v5
	v_pk_mul_f32 v[6:7], v[2:3], v[6:7]
	v_pk_add_f32 v[4:5], v[4:5], 1.0 op_sel_hi:[1,0]
	v_exp_f32_e32 v6, v6
	v_exp_f32_e32 v7, v7
	v_rcp_f32_e32 v4, v4
	v_rcp_f32_e32 v5, v5
	v_pk_add_f32 v[6:7], v[6:7], 1.0 op_sel_hi:[1,0]
	s_nop 0
	v_rcp_f32_e32 v6, v6
	v_rcp_f32_e32 v7, v7
	v_pk_mul_f32 v[0:1], v[0:1], v[4:5]
	v_pk_mul_f32 v[2:3], v[2:3], v[6:7]
	v_cvt_pk_bf16_f32 v4, v0, v1
	v_mul_f32_e32 v0, 0x3d924925, v0
	v_mul_f32_e32 v1, 0x3d924925, v1
	v_cvt_pk_bf16_f32 v5, v2, v3
	v_cvt_pknorm_i16_f32 v0, v0, v1
	v_mul_f32_e32 v1, 0x3d924925, v2
	v_mul_f32_e32 v2, 0x3d924925, v3
	v_cvt_pknorm_i16_f32 v1, v1, v2
	v_pk_add_i16 v0, v0, s54 op_sel_hi:[1,0] clamp
	v_pk_add_i16 v1, v1, s54 op_sel_hi:[1,0] clamp
	global_store_dwordx2 v[8:9], v[4:5], off
	v_perm_b32 v2, v1, v0, s55
	v_mov_b32_e32 v1, s7
	v_subrev_u32_e32 v0, s6, v8
	v_lshrrev_b32_e32 v0, 1, v0
	global_store_dword v0, v2, s[8:9]
	global_load_dwordx2 v[176:177], v253, s[80:81] offset:992
	global_load_dwordx2 v[178:179], v253, s[82:83] offset:992
	s_branch .LBB0_380

; #define LAS __attribute__((address_space(3)))
; template <bool REV> ...
;     constexpr int SG = REV ? -1 : 1;
;     constexpr int TSTEP = SG * 64 * 16, CSTEP16 = SG * 32 * 16, SSTEP = SG * 16;
;     const float nli = -li;
;     const int nl = lane & 31, hl = lane >> 5, tk = lane & 15, kq = lane >> 4;
;     const bf16* pA = U + gbase + SG * (2 * nl + hl) * 16;
;     const bf16* pB = U + gbase + SG * (2 * tk + (kq >> 1)) * 16 + 8 * (kq & 1);
;     const bf16* pU = U + gbase + SG * (2 * tk) * 16 + 4 * kq;
;     bf16* pY = YA + gbase + SG * (2 * tk) * 16 + 4 * kq;
;     bf16x8 A0 = *(const bf16x8*)pA, A1 = *(const bf16x8*)(pA + 8);
;     bf16x8 Ub[2]; Ub[0] = *(const bf16x8*)pB; Ub[1] = *(const bf16x8*)(pB + CSTEP16);
;     u32x2 pv[2][2], uv[2][2];
; #pragma unroll
;     for (int th = 0; th < 2; ++th)
; #pragma unroll
;         for (int sx = 0; sx < 2; ++sx) { pv[th][sx] = (u32x2){0u, 0u}; uv[th][sx] = (u32x2){0u, 0u}; }
;     const f32x2 dsk01 = (f32x2){dsk[0], dsk[1]}, dsk23 = (f32x2){dsk[2], dsk[3]};
;     LAS unsigned* wbase = (LAS unsigned*)(my + ((lane & 3) << 2));
; __device__ __forceinline__ void s5_phase(const Args& a, const Ctx& F) {
;     ...
;     const size_t gbase = ((size_t)(b * NG + g) * SEQ + (d ? SEQ - 1 : 0)) * 16;
;     unsigned char* Y8 = ws + WS_YA8;
;     if (d) s5_latent<true>(U, YA, Y8, gbase, Bf, Cf, Kf, lr, li, hre, him, my, dsk, lane);
;     else s5_latent<false>(U, YA, Y8, gbase, Bf, Cf, Kf, lr, li, hre, him, my, dsk, lane);
.LBB0_401:
	v_lshlrev_b32_e32 v4, 4, v204
	v_lshl_add_u32 v4, v206, 5, v4
	v_ashrrev_i32_e32 v171, 31, v170
	v_ashrrev_i32_e32 v5, 31, v4
	v_lshlrev_b64 v[0:1], 1, v[170:171]
	v_lshlrev_b64 v[4:5], 1, v[4:5]
	v_lshl_add_u64 v[2:3], s[10:11], 0, v[0:1]
	v_lshl_add_u64 v[6:7], s[10:11], 0, v[4:5]
	v_mov_b32_e32 v163, 0
	v_lshl_add_u64 v[6:7], v[6:7], 0, v[162:163]
	global_load_dwordx4 v[152:155], v[2:3], off
	global_load_dwordx4 v[148:151], v[2:3], off offset:16
	global_load_dwordx4 v[144:147], v[6:7], off
	global_load_dwordx4 v[140:143], v[6:7], off offset:1024
	s_add_i32 s0, s19, s33
	s_add_i32 s0, s0, s34
	s_ashr_i32 s1, s0, 31
	s_lshl_b64 s[0:1], s[0:1], 18
	s_or_b32 s0, s0, s23
	s_add_u32 s10, s30, s0
	s_addc_u32 s11, s31, s1
	v_mov_b32_e32 v169, v163
	v_and_b32_e32 v2, 12, v213
	v_lshl_add_u64 v[182:183], s[10:11], 0, v[0:1]
	v_lshl_add_u64 v[0:1], s[0:1], 0, v[168:169]
	v_add_u32_e32 v2, s35, v2
	v_lshl_add_u64 v[0:1], v[0:1], 0, v[4:5]
	v_lshlrev_b32_e32 v162, 6, v206
	v_ashrrev_i32_e32 v167, 31, v166
	v_lshl_add_u32 v232, v212, 2, v2
	v_lshl_add_u32 v231, v214, 2, v2
	v_lshl_add_u32 v230, v215, 2, v2
	v_lshl_add_u32 v229, v216, 2, v2
	v_lshl_add_u32 v216, v217, 2, v2
	v_lshl_add_u32 v215, v218, 2, v2
	v_lshl_add_u32 v214, v219, 2, v2
	v_lshl_add_u32 v213, v220, 2, v2
	v_lshl_add_u32 v212, v221, 2, v2
	v_lshl_add_u32 v204, v222, 2, v2
	v_lshl_add_u32 v203, v223, 2, v2
	v_lshl_add_u32 v202, v224, 2, v2
	v_lshl_add_u32 v197, v225, 2, v2
	v_lshl_add_u32 v196, v226, 2, v2
	v_lshl_add_u32 v195, v227, 2, v2
	v_lshl_add_u32 v194, v228, 2, v2
	v_xor_b32_e32 v2, v208, v207
	v_xor_b32_e32 v3, v211, v208
	v_xor_b32_e32 v6, v210, v208
	v_xor_b32_e32 v7, v209, v208
	v_bitop3_b32 v8, v208, v207, 8 bitop3:0x36
	v_bitop3_b32 v9, v208, v211, 8 bitop3:0x36
	v_bitop3_b32 v10, v208, v210, 8 bitop3:0x36
	v_bitop3_b32 v11, v208, v209, 8 bitop3:0x36
	v_lshl_add_u64 v[184:185], s[30:31], 0, v[0:1]
	v_lshl_add_u64 v[0:1], s[0:1], 0, v[162:163]
	v_lshlrev_b32_e32 v2, 4, v2
	v_lshlrev_b32_e32 v3, 4, v3
	v_lshlrev_b32_e32 v6, 4, v6
	v_lshlrev_b32_e32 v7, 4, v7
	v_lshlrev_b32_e32 v8, 4, v8
	v_lshlrev_b32_e32 v9, 4, v9
	v_lshlrev_b32_e32 v10, 4, v10
	v_lshlrev_b32_e32 v11, 4, v11
	v_lshl_add_u64 v[0:1], v[166:167], 1, v[0:1]
	v_mov_b32_e32 v162, v163
	s_sub_u32 s76, 0x10000000, s30
	s_add_u32 s78, s30, 0x1bc00000
	s_addc_u32 s79, s31, 0
	s_add_u32 s80, s30, 0x3c400000
	s_addc_u32 s81, s31, 0
	v_lshl_add_u64 v[174:175], s[30:31], 0, v[0:1]
	s_mov_b32 s17, 0
	s_mov_b64 s[10:11], 0
	s_mov_b64 s[12:13], 0x4c400000
	s_mov_b32 s19, 0x2bc00000
	s_mov_b32 s16, 0x3dd2d3e8
	s_mov_b32 s18, 0xc0135761
	v_mov_b32_e32 v254, s18
	s_movk_i32 s33, 0x80
	s_mov_b32 s34, 0x7050301
	s_mov_b64 s[22:23], 0x4c400020
	s_mov_b64 s[38:39], 0x4c400400
	s_mov_b64 s[40:41], 0x4c400420
	v_add_u32_e32 v200, v205, v2
	v_add_u32_e32 v201, v205, v3
	v_add_u32_e32 v199, v205, v6
	v_add_u32_e32 v198, v205, v7
	v_add_u32_e32 v192, v205, v8
	v_add_u32_e32 v193, v205, v9
	v_add_u32_e32 v190, v205, v10
	v_add_u32_e32 v191, v205, v11
	v_mov_b64_e32 v[170:171], v[162:163]
	v_mov_b64_e32 v[176:177], v[162:163]
	v_mov_b64_e32 v[180:181], v[162:163]
	v_mov_b64_e32 v[166:167], v[162:163]
	v_mov_b64_e32 v[168:169], v[162:163]
	v_mov_b64_e32 v[172:173], v[162:163]
	v_mov_b64_e32 v[178:179], v[162:163]
	s_waitcnt vmcnt(0)
	s_branch .LBB0_403

; __device__ __forceinline__ unsigned cvt_pk_bf16(float lo, float hi) { unsigned r; asm volatile("v_cvt_pk_bf16_f32 %0, %1, %2" : "=v"(r) : "v"(lo), "v"(hi)); return r; }
; __device__ __forceinline__ float bf_lo(unsigned w) { return __uint_as_float(w << 16); }
; __device__ __forceinline__ float bf_hi(unsigned w) { return __uint_as_float(w & 0xffff0000u); }
; __device__ __forceinline__ f32x2 gelu2(f32x2 v) {
;     const f32x2 t = v * v, w = t * (-0.10294324f) + (-2.3022082f), a = v * w;
;     f32x2 e; e.x = __builtin_amdgcn_exp2f(a.x); e.y = __builtin_amdgcn_exp2f(a.y);
;     const f32x2 q = e + 1.0f; f32x2 r; r.x = __builtin_amdgcn_rcpf(q.x); r.y = __builtin_amdgcn_rcpf(q.y);
;     return v * r;
; }
; template <bool REV> ...
;     ...
;                 else { const u32x2 p = pv[th][sx], u = uv[th][sx];
;                     const f32x2 v01 = (f32x2){y[0], y[1]} + (f32x2){bf_lo(p.x), bf_hi(p.x)} + dsk01 * (f32x2){bf_lo(u.x), bf_hi(u.x)};
;                     const f32x2 v23 = (f32x2){y[2], y[3]} + (f32x2){bf_lo(p.y), bf_hi(p.y)} + dsk23 * (f32x2){bf_lo(u.y), bf_hi(u.y)};
;                     const f32x2 o01 = gelu2(v01), o23 = gelu2(v23);
;                     u32x2 w; w.x = cvt_pk_bf16(o01.x, o01.y); w.y = cvt_pk_bf16(o23.x, o23.y); *(u32x2*)yo = w;
;                     { const unsigned x8 = pack_i8x4(o01.x, o01.y, o23.x, o23.y, 1.0f / YA8_R);
;                       *(unsigned*)(Y8 + (yo - YA)) = x8; }
;                     pv[th][sx] = *(const u32x2*)(yo + adv); uv[th][sx] = *(const u32x2*)(pU + th * CSTEP16 + sx * SSTEP + adv); }
.LBB0_407:
	s_andn2_b64 vcc, exec, s[0:1]
	s_cbranch_vccnz .LBB0_409
	v_lshlrev_b32_e32 v24, 16, v180
	v_and_b32_e32 v25, 0xffff0000, v180
	s_nop 2
	v_pk_add_f32 v[20:21], v[20:21], v[24:25]
	v_lshlrev_b32_e32 v24, 16, v178
	v_and_b32_e32 v25, 0xffff0000, v178
	v_pk_fma_f32 v[20:21], v[64:65], v[24:25], v[20:21]
	v_lshlrev_b32_e32 v24, 16, v181
	v_and_b32_e32 v25, 0xffff0000, v181
	v_pk_add_f32 v[22:23], v[22:23], v[24:25]
	v_lshlrev_b32_e32 v24, 16, v179
	v_and_b32_e32 v25, 0xffff0000, v179
	v_pk_fma_f32 v[22:23], v[66:67], v[24:25], v[22:23]
	v_pk_mul_f32 v[24:25], v[20:21], v[20:21]
	v_pk_fma_f32 v[24:25], v[24:25], s[16:17], v[254:255] op_sel_hi:[1,0,0] neg_lo:[1,0,0] neg_hi:[1,0,0]
	v_pk_mul_f32 v[28:29], v[22:23], v[22:23]
	v_pk_mul_f32 v[24:25], v[20:21], v[24:25]
	v_pk_fma_f32 v[26:27], v[28:29], s[16:17], v[254:255] op_sel_hi:[1,0,0] neg_lo:[1,0,0] neg_hi:[1,0,0]
	v_exp_f32_e32 v24, v24
	v_exp_f32_e32 v25, v25
	v_pk_mul_f32 v[26:27], v[22:23], v[26:27]
	v_pk_add_f32 v[24:25], v[24:25], 1.0 op_sel_hi:[1,0]
	v_exp_f32_e32 v26, v26
	v_exp_f32_e32 v27, v27
	v_rcp_f32_e32 v24, v24
	v_rcp_f32_e32 v25, v25
	v_pk_add_f32 v[26:27], v[26:27], 1.0 op_sel_hi:[1,0]
	s_nop 0
	v_rcp_f32_e32 v26, v26
	v_rcp_f32_e32 v27, v27
	v_pk_mul_f32 v[20:21], v[20:21], v[24:25]
	v_pk_mul_f32 v[22:23], v[22:23], v[26:27]
	v_cvt_pk_bf16_f32 v24, v20, v21
	v_mul_f32_e32 v14, 0x3d924925, v20
	v_mul_f32_e32 v20, 0x3d924925, v21
	v_cvt_pknorm_i16_f32 v14, v14, v20
	v_mul_f32_e32 v20, 0x3d924925, v22
	v_mul_f32_e32 v21, 0x3d924925, v23
	v_cvt_pknorm_i16_f32 v20, v20, v21
	v_pk_add_i16 v14, v14, s33 op_sel_hi:[1,0] clamp
	v_pk_add_i16 v20, v20, s33 op_sel_hi:[1,0] clamp
	v_mov_b32_e32 v21, s7
	v_perm_b32 v14, v20, v14, s34
	v_subrev_u32_e32 v20, s6, v188
	v_cvt_pk_bf16_f32 v25, v22, v23
	global_store_dwordx2 v[188:189], v[24:25], off
	v_lshrrev_b32_e32 v20, 1, v20
	global_store_dword v20, v14, s[8:9]
	global_load_dwordx2 v[180:181], v253, s[80:81] offset:2048
	global_load_dwordx2 v[178:179], v253, s[78:79] offset:2048

; __device__ __forceinline__ unsigned cvt_pk_bf16(float lo, float hi) { unsigned r; asm volatile("v_cvt_pk_bf16_f32 %0, %1, %2" : "=v"(r) : "v"(lo), "v"(hi)); return r; }
; __device__ __forceinline__ float bf_lo(unsigned w) { return __uint_as_float(w << 16); }
; __device__ __forceinline__ float bf_hi(unsigned w) { return __uint_as_float(w & 0xffff0000u); }
; __device__ __forceinline__ f32x2 gelu2(f32x2 v) {
;     const f32x2 t = v * v, w = t * (-0.10294324f) + (-2.3022082f), a = v * w;
;     f32x2 e; e.x = __builtin_amdgcn_exp2f(a.x); e.y = __builtin_amdgcn_exp2f(a.y);
;     const f32x2 q = e + 1.0f; f32x2 r; r.x = __builtin_amdgcn_rcpf(q.x); r.y = __builtin_amdgcn_rcpf(q.y);
;     return v * r;
; }
; template <bool REV> ...
;     ...
;                 else { const u32x2 p = pv[th][sx], u = uv[th][sx];
;                     const f32x2 v01 = (f32x2){y[0], y[1]} + (f32x2){bf_lo(p.x), bf_hi(p.x)} + dsk01 * (f32x2){bf_lo(u.x), bf_hi(u.x)};
;                     const f32x2 v23 = (f32x2){y[2], y[3]} + (f32x2){bf_lo(p.y), bf_hi(p.y)} + dsk23 * (f32x2){bf_lo(u.y), bf_hi(u.y)};
;                     const f32x2 o01 = gelu2(v01), o23 = gelu2(v23);
;                     u32x2 w; w.x = cvt_pk_bf16(o01.x, o01.y); w.y = cvt_pk_bf16(o23.x, o23.y); *(u32x2*)yo = w;
;                     { const unsigned x8 = pack_i8x4(o01.x, o01.y, o23.x, o23.y, 1.0f / YA8_R);
;                       *(unsigned*)(Y8 + (yo - YA)) = x8; }
;                     pv[th][sx] = *(const u32x2*)(yo + adv); uv[th][sx] = *(const u32x2*)(pU + th * CSTEP16 + sx * SSTEP + adv); }
.LBB0_411:
	s_andn2_b64 vcc, exec, s[46:47]
	s_cbranch_vccnz .LBB0_413
	v_lshlrev_b32_e32 v4, 16, v176
	v_and_b32_e32 v5, 0xffff0000, v176
	s_nop 2
	v_pk_add_f32 v[0:1], v[0:1], v[4:5]
	v_lshlrev_b32_e32 v4, 16, v172
	v_and_b32_e32 v5, 0xffff0000, v172
	v_pk_fma_f32 v[0:1], v[64:65], v[4:5], v[0:1]
	v_lshlrev_b32_e32 v4, 16, v177
	v_and_b32_e32 v5, 0xffff0000, v177
	v_pk_add_f32 v[2:3], v[2:3], v[4:5]
	v_lshlrev_b32_e32 v4, 16, v173
	v_and_b32_e32 v5, 0xffff0000, v173
	v_pk_fma_f32 v[2:3], v[66:67], v[4:5], v[2:3]
	v_pk_mul_f32 v[4:5], v[0:1], v[0:1]
	v_pk_fma_f32 v[4:5], v[4:5], s[16:17], v[254:255] op_sel_hi:[1,0,0] neg_lo:[1,0,0] neg_hi:[1,0,0]
	v_pk_mul_f32 v[10:11], v[2:3], v[2:3]
	v_pk_mul_f32 v[4:5], v[0:1], v[4:5]
	v_pk_fma_f32 v[6:7], v[10:11], s[16:17], v[254:255] op_sel_hi:[1,0,0] neg_lo:[1,0,0] neg_hi:[1,0,0]
	v_exp_f32_e32 v4, v4
	v_exp_f32_e32 v5, v5
	v_pk_mul_f32 v[6:7], v[2:3], v[6:7]
	v_pk_add_f32 v[4:5], v[4:5], 1.0 op_sel_hi:[1,0]
	v_exp_f32_e32 v6, v6
	v_exp_f32_e32 v7, v7
	v_rcp_f32_e32 v4, v4
	v_rcp_f32_e32 v5, v5
	v_pk_add_f32 v[6:7], v[6:7], 1.0 op_sel_hi:[1,0]
	s_nop 0
	v_rcp_f32_e32 v6, v6
	v_rcp_f32_e32 v7, v7
	v_pk_mul_f32 v[0:1], v[0:1], v[4:5]
	v_pk_mul_f32 v[2:3], v[2:3], v[6:7]
	v_cvt_pk_bf16_f32 v4, v0, v1
	v_mul_f32_e32 v0, 0x3d924925, v0
	v_mul_f32_e32 v1, 0x3d924925, v1
	v_cvt_pk_bf16_f32 v5, v2, v3
	v_cvt_pknorm_i16_f32 v0, v0, v1
	v_mul_f32_e32 v1, 0x3d924925, v2
	v_mul_f32_e32 v2, 0x3d924925, v3
	v_cvt_pknorm_i16_f32 v1, v1, v2
	v_pk_add_i16 v0, v0, s33 op_sel_hi:[1,0] clamp
	v_pk_add_i16 v1, v1, s33 op_sel_hi:[1,0] clamp
	global_store_dwordx2 v[8:9], v[4:5], off
	v_perm_b32 v2, v1, v0, s34
	v_subrev_u32_e32 v0, s6, v8
	v_lshrrev_b32_e32 v0, 1, v0
	global_store_dword v0, v2, s[8:9]
	global_load_dwordx2 v[176:177], v253, s[80:81] offset:2080
	global_load_dwordx2 v[172:173], v253, s[78:79] offset:2080

; __device__ __forceinline__ unsigned cvt_pk_bf16(float lo, float hi) { unsigned r; asm volatile("v_cvt_pk_bf16_f32 %0, %1, %2" : "=v"(r) : "v"(lo), "v"(hi)); return r; }
; __device__ __forceinline__ float bf_lo(unsigned w) { return __uint_as_float(w << 16); }
; __device__ __forceinline__ float bf_hi(unsigned w) { return __uint_as_float(w & 0xffff0000u); }
; __device__ __forceinline__ f32x2 gelu2(f32x2 v) {
;     const f32x2 t = v * v, w = t * (-0.10294324f) + (-2.3022082f), a = v * w;
;     f32x2 e; e.x = __builtin_amdgcn_exp2f(a.x); e.y = __builtin_amdgcn_exp2f(a.y);
;     const f32x2 q = e + 1.0f; f32x2 r; r.x = __builtin_amdgcn_rcpf(q.x); r.y = __builtin_amdgcn_rcpf(q.y);
;     return v * r;
; }
; template <bool REV> ...
;     ...
;                 else { const u32x2 p = pv[th][sx], u = uv[th][sx];
;                     const f32x2 v01 = (f32x2){y[0], y[1]} + (f32x2){bf_lo(p.x), bf_hi(p.x)} + dsk01 * (f32x2){bf_lo(u.x), bf_hi(u.x)};
;                     const f32x2 v23 = (f32x2){y[2], y[3]} + (f32x2){bf_lo(p.y), bf_hi(p.y)} + dsk23 * (f32x2){bf_lo(u.y), bf_hi(u.y)};
;                     const f32x2 o01 = gelu2(v01), o23 = gelu2(v23);
;                     u32x2 w; w.x = cvt_pk_bf16(o01.x, o01.y); w.y = cvt_pk_bf16(o23.x, o23.y); *(u32x2*)yo = w;
;                     { const unsigned x8 = pack_i8x4(o01.x, o01.y, o23.x, o23.y, 1.0f / YA8_R);
;                       *(unsigned*)(Y8 + (yo - YA)) = x8; }
;                     pv[th][sx] = *(const u32x2*)(yo + adv); uv[th][sx] = *(const u32x2*)(pU + th * CSTEP16 + sx * SSTEP + adv); }
.LBB0_415:
	s_andn2_b64 vcc, exec, s[42:43]
	s_cbranch_vccnz .LBB0_417
	v_lshlrev_b32_e32 v28, 16, v170
	v_and_b32_e32 v29, 0xffff0000, v170
	s_nop 2
	v_pk_add_f32 v[20:21], v[20:21], v[28:29]
	v_lshlrev_b32_e32 v28, 16, v168
	v_and_b32_e32 v29, 0xffff0000, v168
	v_pk_fma_f32 v[20:21], v[64:65], v[28:29], v[20:21]
	v_lshlrev_b32_e32 v28, 16, v171
	v_and_b32_e32 v29, 0xffff0000, v171
	v_pk_add_f32 v[22:23], v[22:23], v[28:29]
	v_lshlrev_b32_e32 v28, 16, v169
	v_and_b32_e32 v29, 0xffff0000, v169
	v_pk_fma_f32 v[22:23], v[66:67], v[28:29], v[22:23]
	v_pk_mul_f32 v[28:29], v[20:21], v[20:21]
	v_pk_fma_f32 v[28:29], v[28:29], s[16:17], v[254:255] op_sel_hi:[1,0,0] neg_lo:[1,0,0] neg_hi:[1,0,0]
	v_pk_mul_f32 v[34:35], v[22:23], v[22:23]
	v_pk_mul_f32 v[28:29], v[20:21], v[28:29]
	v_pk_fma_f32 v[32:33], v[34:35], s[16:17], v[254:255] op_sel_hi:[1,0,0] neg_lo:[1,0,0] neg_hi:[1,0,0]
	v_exp_f32_e32 v28, v28
	v_exp_f32_e32 v29, v29
	v_pk_mul_f32 v[32:33], v[22:23], v[32:33]
	v_pk_add_f32 v[28:29], v[28:29], 1.0 op_sel_hi:[1,0]
	v_exp_f32_e32 v32, v32
	v_exp_f32_e32 v33, v33
	v_rcp_f32_e32 v28, v28
	v_rcp_f32_e32 v29, v29
	v_pk_add_f32 v[32:33], v[32:33], 1.0 op_sel_hi:[1,0]
	s_nop 0
	v_rcp_f32_e32 v32, v32
	v_rcp_f32_e32 v33, v33
	v_pk_mul_f32 v[20:21], v[20:21], v[28:29]
	v_pk_mul_f32 v[22:23], v[22:23], v[32:33]
	v_cvt_pk_bf16_f32 v28, v20, v21
	v_mul_f32_e32 v14, 0x3d924925, v20
	v_mul_f32_e32 v20, 0x3d924925, v21
	v_cvt_pknorm_i16_f32 v14, v14, v20
	v_mul_f32_e32 v20, 0x3d924925, v22
	v_mul_f32_e32 v21, 0x3d924925, v23
	v_cvt_pknorm_i16_f32 v20, v20, v21
	v_pk_add_i16 v14, v14, s33 op_sel_hi:[1,0] clamp
	v_pk_add_i16 v20, v20, s33 op_sel_hi:[1,0] clamp
	v_mov_b32_e32 v21, s7
	v_perm_b32 v14, v20, v14, s34
	v_subrev_u32_e32 v20, s6, v26
	v_cvt_pk_bf16_f32 v29, v22, v23
	global_store_dwordx2 v[26:27], v[28:29], off
	v_lshrrev_b32_e32 v20, 1, v20
	global_store_dword v20, v14, s[8:9]
	global_load_dwordx2 v[170:171], v253, s[80:81] offset:3072
	global_load_dwordx2 v[168:169], v253, s[78:79] offset:3072

; __device__ __forceinline__ unsigned cvt_pk_bf16(float lo, float hi) { unsigned r; asm volatile("v_cvt_pk_bf16_f32 %0, %1, %2" : "=v"(r) : "v"(lo), "v"(hi)); return r; }
; __device__ __forceinline__ float bf_lo(unsigned w) { return __uint_as_float(w << 16); }
; __device__ __forceinline__ float bf_hi(unsigned w) { return __uint_as_float(w & 0xffff0000u); }
; __device__ __forceinline__ f32x2 gelu2(f32x2 v) {
;     const f32x2 t = v * v, w = t * (-0.10294324f) + (-2.3022082f), a = v * w;
;     f32x2 e; e.x = __builtin_amdgcn_exp2f(a.x); e.y = __builtin_amdgcn_exp2f(a.y);
;     const f32x2 q = e + 1.0f; f32x2 r; r.x = __builtin_amdgcn_rcpf(q.x); r.y = __builtin_amdgcn_rcpf(q.y);
;     return v * r;
; }
; template <bool REV> ...
;     ...
;                 else { const u32x2 p = pv[th][sx], u = uv[th][sx];
;                     const f32x2 v01 = (f32x2){y[0], y[1]} + (f32x2){bf_lo(p.x), bf_hi(p.x)} + dsk01 * (f32x2){bf_lo(u.x), bf_hi(u.x)};
;                     const f32x2 v23 = (f32x2){y[2], y[3]} + (f32x2){bf_lo(p.y), bf_hi(p.y)} + dsk23 * (f32x2){bf_lo(u.y), bf_hi(u.y)};
;                     const f32x2 o01 = gelu2(v01), o23 = gelu2(v23);
;                     u32x2 w; w.x = cvt_pk_bf16(o01.x, o01.y); w.y = cvt_pk_bf16(o23.x, o23.y); *(u32x2*)yo = w;
;                     { const unsigned x8 = pack_i8x4(o01.x, o01.y, o23.x, o23.y, 1.0f / YA8_R);
;                       *(unsigned*)(Y8 + (yo - YA)) = x8; }
;                     pv[th][sx] = *(const u32x2*)(yo + adv); uv[th][sx] = *(const u32x2*)(pU + th * CSTEP16 + sx * SSTEP + adv); }
.LBB0_419:
	s_andn2_b64 vcc, exec, s[42:43]
	s_cbranch_vccnz .LBB0_402
	v_lshlrev_b32_e32 v4, 16, v162
	v_and_b32_e32 v5, 0xffff0000, v162
	s_nop 2
	v_pk_add_f32 v[0:1], v[0:1], v[4:5]
	v_lshlrev_b32_e32 v4, 16, v166
	v_and_b32_e32 v5, 0xffff0000, v166
	v_pk_fma_f32 v[0:1], v[64:65], v[4:5], v[0:1]
	v_lshlrev_b32_e32 v4, 16, v163
	v_and_b32_e32 v5, 0xffff0000, v163
	v_pk_add_f32 v[2:3], v[2:3], v[4:5]
	v_lshlrev_b32_e32 v4, 16, v167
	v_and_b32_e32 v5, 0xffff0000, v167
	v_pk_fma_f32 v[2:3], v[66:67], v[4:5], v[2:3]
	v_pk_mul_f32 v[4:5], v[0:1], v[0:1]
	v_pk_fma_f32 v[4:5], v[4:5], s[16:17], v[254:255] op_sel_hi:[1,0,0] neg_lo:[1,0,0] neg_hi:[1,0,0]
	v_pk_mul_f32 v[10:11], v[2:3], v[2:3]
	v_pk_mul_f32 v[4:5], v[0:1], v[4:5]
	v_pk_fma_f32 v[6:7], v[10:11], s[16:17], v[254:255] op_sel_hi:[1,0,0] neg_lo:[1,0,0] neg_hi:[1,0,0]
	v_exp_f32_e32 v4, v4
	v_exp_f32_e32 v5, v5
	v_pk_mul_f32 v[6:7], v[2:3], v[6:7]
	v_pk_add_f32 v[4:5], v[4:5], 1.0 op_sel_hi:[1,0]
	v_exp_f32_e32 v6, v6
	v_exp_f32_e32 v7, v7
	v_rcp_f32_e32 v4, v4
	v_rcp_f32_e32 v5, v5
	v_pk_add_f32 v[6:7], v[6:7], 1.0 op_sel_hi:[1,0]
	s_nop 0
	v_rcp_f32_e32 v6, v6
	v_rcp_f32_e32 v7, v7
	v_pk_mul_f32 v[0:1], v[0:1], v[4:5]
	v_pk_mul_f32 v[2:3], v[2:3], v[6:7]
	v_cvt_pk_bf16_f32 v4, v0, v1
	v_mul_f32_e32 v0, 0x3d924925, v0
	v_mul_f32_e32 v1, 0x3d924925, v1
	v_cvt_pk_bf16_f32 v5, v2, v3
	v_cvt_pknorm_i16_f32 v0, v0, v1
	v_mul_f32_e32 v1, 0x3d924925, v2
	v_mul_f32_e32 v2, 0x3d924925, v3
	v_cvt_pknorm_i16_f32 v1, v1, v2
	v_pk_add_i16 v0, v0, s33 op_sel_hi:[1,0] clamp
	v_pk_add_i16 v1, v1, s33 op_sel_hi:[1,0] clamp
	global_store_dwordx2 v[8:9], v[4:5], off
	v_perm_b32 v2, v1, v0, s34
	v_mov_b32_e32 v1, s7
	v_subrev_u32_e32 v0, s6, v8
	v_lshrrev_b32_e32 v0, 1, v0
	global_store_dword v0, v2, s[8:9]
	global_load_dwordx2 v[162:163], v253, s[80:81] offset:3104
	global_load_dwordx2 v[166:167], v253, s[78:79] offset:3104
	s_branch .LBB0_402
